# deferred transposes rebalanced: the last 3072 items (37 MB) of layer-0 W2 moved from the layer-0 in-proj tail to the layer-0 MLP-up tail
# speedup vs baseline: 1.0037x; 1.0037x over previous
.Ltr_a_m3_end:
	s_load_dwordx2 s[64:65], s[76:77], 0xa8
	s_waitcnt lgkmcnt(0)
	s_mul_i32 s69, s81, 0x4000000
	s_add_u32 s64, s64, s69
	s_addc_u32 s65, s65, 0
	s_mul_i32 s69, s81, 0x5780000
	s_add_u32 s69, s69, 0x3880000
	s_add_u32 s66, s82, s69
	s_addc_u32 s67, s83, 0
	s_mov_b32 s68, 0x4000
	s_mov_b32 s61, 5120
	s_cmp_eq_u32 s81, 1
	s_cmov_b32 s61, 8192
	s_mov_b32 s60, s63
	v_mov_b32_e32 v2, 0x800
	v_mul_u32_u24_e32 v2, v2, v55
	v_add_lshl_u32 v2, v2, v54, 2
	v_mov_b32_e32 v52, 0x4000
	v_mul_u32_u24_e32 v52, v52, v54
	v_lshl_add_u32 v52, v55, 6, v52

.LBB0_1147:
	s_cmp_lt_u32 s2, 128
	s_cbranch_scc1 .Ltr_b_done
	s_cmp_ge_i32 s44, 11
	s_cbranch_scc1 .Ltr_b_done
	s_lshl_b32 vcc_lo, s3, 10
	s_mov_b32 vcc_hi, m0
	s_mov_b32 m0, vcc_lo
	s_nop 0
	ds_write_addtid_b32 v0 offset:0
	ds_write_addtid_b32 v1 offset:256
	ds_write_addtid_b32 v2 offset:512
	ds_write_addtid_b32 v3 offset:768
	s_waitcnt lgkmcnt(0)
	v_mbcnt_lo_u32_b32 v2, -1, 0
	v_mbcnt_hi_u32_b32 v2, -1, v2
	s_mul_i32 vcc_lo, s3, 13312
	s_add_i32 vcc_lo, vcc_lo, 8192
	v_lshl_add_u32 v0, v2, 4, vcc_lo
	ds_write_b128 v0, v[4:7]
	ds_write_b128 v0, v[8:11] offset:1024
	ds_write_b128 v0, v[12:15] offset:2048
	ds_write_b128 v0, v[16:19] offset:3072
	ds_write_b128 v0, v[20:23] offset:4096
	ds_write_b128 v0, v[24:27] offset:5120
	ds_write_b128 v0, v[28:31] offset:6144
	ds_write_b128 v0, v[32:35] offset:7168
	ds_write_b128 v0, v[36:39] offset:8192
	ds_write_b128 v0, v[40:43] offset:9216
	ds_write_b128 v0, v[44:47] offset:10240
	ds_write_b128 v0, v[48:51] offset:11264
	ds_write_b128 v0, v[52:55] offset:12288
	s_waitcnt lgkmcnt(0)
	v_writelane_b32 v1, s60, 0
	v_writelane_b32 v1, s61, 1
	v_writelane_b32 v1, s62, 2
	v_writelane_b32 v1, s63, 3
	v_writelane_b32 v1, s64, 4
	v_writelane_b32 v1, s65, 5
	v_writelane_b32 v1, s66, 6
	v_writelane_b32 v1, s67, 7
	v_writelane_b32 v1, s68, 8
	v_writelane_b32 v1, s69, 9
	v_writelane_b32 v1, s70, 10
	v_writelane_b32 v1, s71, 11
	v_writelane_b32 v1, s72, 12
	v_writelane_b32 v1, s73, 13
	v_writelane_b32 v1, s74, 14
	v_writelane_b32 v1, s75, 15
	v_writelane_b32 v1, s76, 16
	v_writelane_b32 v1, s77, 17
	v_writelane_b32 v1, s78, 18
	v_writelane_b32 v1, s79, 19
	v_writelane_b32 v1, s80, 20
	v_writelane_b32 v1, s81, 21
	v_writelane_b32 v1, s82, 22
	v_writelane_b32 v1, s83, 23
	v_writelane_b32 v1, vcc_hi, 24
	v_mov_b32_e32 v53, v2
	v_and_b32_e32 v54, 31, v53
	v_lshrrev_b32_e32 v55, 5, v53
	v_readlane_b32 s76, v248, 0
	v_readlane_b32 s77, v248, 1
	s_nop 3
	s_sub_u32 s76, s76, 0xd0
	s_subb_u32 s77, s77, 0
	s_sub_u32 s63, s2, 128
	s_lshl_b32 s63, s63, 3
	s_add_u32 s63, s63, s3
	s_sub_u32 s62, s34, 128
	s_lshl_b32 s62, s62, 3
	s_load_dwordx2 s[82:83], s[76:77], 0xc0
	s_load_dwordx2 s[64:65], s[76:77], 0xa8
	s_waitcnt lgkmcnt(0)
	s_add_u32 s64, s64, 0x0
	s_addc_u32 s65, s65, 0
	s_mov_b32 s69, 0x3880000
	s_add_u32 s66, s82, s69
	s_addc_u32 s67, s83, 0
	s_mov_b32 s68, 0x4000
	s_mov_b32 s61, 8192
	s_add_u32 s60, s63, 5120
	v_mov_b32_e32 v2, 0x800
	v_mul_u32_u24_e32 v2, v2, v55
	v_add_lshl_u32 v2, v2, v54, 2
	v_mov_b32_e32 v52, 0x4000
	v_mul_u32_u24_e32 v52, v52, v54
	v_lshl_add_u32 v52, v55, 6, v52

.Ltr_b_m0_end:
	s_load_dwordx2 s[64:65], s[76:77], 0x40
	s_waitcnt lgkmcnt(0)
	s_add_u32 s64, s64, 0x1680000
	s_addc_u32 s65, s65, 0
	s_mov_b32 s69, 0x5880000
	s_add_u32 s66, s82, s69
	s_addc_u32 s67, s83, 0
	s_mov_b32 s68, 0x5a00
	s_mov_b32 s61, 2880
	s_mov_b32 s60, s63
	v_mov_b32_e32 v2, 0xb40
	v_mul_u32_u24_e32 v2, v2, v55
	v_add_lshl_u32 v2, v2, v54, 2
	v_mov_b32_e32 v52, 0x1000
	v_mul_u32_u24_e32 v52, v52, v54
	v_lshl_add_u32 v52, v55, 6, v52
